# selection-walk fast path: one select on the row max instead of 16 per-score selects, plus packed scale-subtract fmas
# speedup vs baseline: 1.0118x; 1.0118x over previous
.LBB0_1265:
	v_cmp_lt_i32_e32 vcc, -1, v199
	s_nop 1
	v_max3_f32 v8, v126, s96, v127
	v_max3_f32 v8, v8, v128, v129
	v_max3_f32 v8, v8, v82, v83
	v_max3_f32 v8, v8, v84, v85
	v_max3_f32 v8, v8, v74, v75
	v_max3_f32 v8, v8, v76, v77
	v_max3_f32 v8, v8, v122, v123
	v_max3_f32 v8, v8, v124, v125
	v_cndmask_b32_e32 v8, v246, v8, vcc
	v_mov_b32_e32 v9, v8
	s_nop 1
	v_permlane16_swap_b32_e32 v8, v9
	v_max_f32_e32 v9, v8, v9
	v_mov_b32_e32 v8, v9
	s_nop 1
	v_permlane32_swap_b32_e32 v9, v8
	v_max3_f32 v10, v192, v9, v8
	v_max_f32_e32 v11, 0xe0ad78ec, v10
	v_mul_f32_e32 v11, s70, v11
	v_sub_f32_e32 v12, v192, v10
	v_cndmask_b32_e64 v11, -v246, v11, vcc
	v_mul_f32_e32 v12, 0x3e38aa3b, v12
	v_mul_f32_e32 v14, s70, v125
	v_exp_f32_e32 v12, v12
	v_sub_f32_e32 v14, v14, v11
	v_pk_fma_f32 v[126:127], v[126:127], s[70:71], v[10:11] op_sel:[0,0,1] op_sel_hi:[1,0,1] neg_lo:[0,0,1] neg_hi:[0,0,1]
	v_exp_f32_e32 v126, v126
	v_exp_f32_e32 v127, v127
	v_add_f32_e32 v13, 0, v126
	v_pk_fma_f32 v[128:129], v[128:129], s[70:71], v[10:11] op_sel:[0,0,1] op_sel_hi:[1,0,1] neg_lo:[0,0,1] neg_hi:[0,0,1]
	v_exp_f32_e32 v128, v128
	v_add_f32_e32 v13, v127, v13
	v_exp_f32_e32 v129, v129
	v_add_f32_e32 v13, v128, v13
	v_fma_f32 v0, v82, s70, -v11
	v_exp_f32_e32 v0, v0
	v_add_f32_e32 v13, v129, v13
	v_fma_f32 v1, v83, s70, -v11
	v_exp_f32_e32 v1, v1
	v_add_f32_e32 v13, v0, v13
	v_fma_f32 v2, v84, s70, -v11
	v_exp_f32_e32 v2, v2
	v_add_f32_e32 v13, v1, v13
	v_fma_f32 v3, v85, s70, -v11
	v_exp_f32_e32 v3, v3
	v_add_f32_e32 v13, v2, v13
	v_fma_f32 v4, v74, s70, -v11
	v_exp_f32_e32 v4, v4
	v_add_f32_e32 v13, v3, v13
	v_fma_f32 v5, v75, s70, -v11
	v_exp_f32_e32 v5, v5
	v_add_f32_e32 v13, v4, v13
	v_fma_f32 v6, v76, s70, -v11
	v_exp_f32_e32 v6, v6
	v_add_f32_e32 v13, v5, v13
	v_fma_f32 v7, v77, s70, -v11
	v_exp_f32_e32 v7, v7
	v_add_f32_e32 v13, v6, v13
	v_pk_fma_f32 v[122:123], v[122:123], s[70:71], v[10:11] op_sel:[0,0,1] op_sel_hi:[1,0,1] neg_lo:[0,0,1] neg_hi:[0,0,1]
	v_exp_f32_e32 v122, v122
	v_add_f32_e32 v13, v7, v13
	v_exp_f32_e32 v123, v123
	v_add_f32_e32 v13, v122, v13
	v_fma_f32 v124, v124, s70, -v11
	v_exp_f32_e32 v124, v124
	v_add_f32_e32 v13, v123, v13
	v_exp_f32_e32 v125, v14
	v_add_f32_e32 v13, v124, v13
	v_add_f32_e32 v13, v125, v13
	v_fma_f32 v133, v133, v12, v13
	v_pk_mul_f32 v[72:73], v[72:73], v[12:13] op_sel_hi:[1,0]
	v_pk_mul_f32 v[70:71], v[70:71], v[12:13] op_sel_hi:[1,0]
	v_pk_mul_f32 v[64:65], v[64:65], v[12:13] op_sel_hi:[1,0]
	v_pk_mul_f32 v[62:63], v[62:63], v[12:13] op_sel_hi:[1,0]
	v_pk_mul_f32 v[56:57], v[56:57], v[12:13] op_sel_hi:[1,0]
	v_pk_mul_f32 v[54:55], v[54:55], v[12:13] op_sel_hi:[1,0]
	v_pk_mul_f32 v[48:49], v[48:49], v[12:13] op_sel_hi:[1,0]
	v_pk_mul_f32 v[46:47], v[46:47], v[12:13] op_sel_hi:[1,0]
	v_mov_b32_e32 v192, v10
	v_cvt_pk_bf16_f32 v74, v126, v127
	v_cvt_pk_bf16_f32 v75, v128, v129
	v_cvt_pk_bf16_f32 v76, v0, v1
	v_cvt_pk_bf16_f32 v77, v2, v3
	v_cvt_pk_bf16_f32 v82, v4, v5
	v_cvt_pk_bf16_f32 v83, v6, v7
	v_cvt_pk_bf16_f32 v84, v122, v123
	v_cvt_pk_bf16_f32 v85, v124, v125
	s_branch .LBB0_1267

.LBB0_1270:
	v_cmp_lt_i32_e32 vcc, -1, v94
	s_nop 1
	v_max3_f32 v8, v98, s96, v99
	v_max3_f32 v8, v8, v100, v101
	v_max3_f32 v8, v8, v86, v87
	v_max3_f32 v8, v8, v88, v89
	v_max3_f32 v8, v8, v78, v79
	v_max3_f32 v8, v8, v80, v81
	v_max3_f32 v8, v8, v90, v91
	v_max3_f32 v8, v8, v92, v93
	v_cndmask_b32_e32 v8, v246, v8, vcc
	v_mov_b32_e32 v9, v8
	s_nop 1
	v_permlane16_swap_b32_e32 v8, v9
	v_max_f32_e32 v9, v8, v9
	v_mov_b32_e32 v8, v9
	s_nop 1
	v_permlane32_swap_b32_e32 v9, v8
	v_max3_f32 v10, v191, v9, v8
	v_max_f32_e32 v11, 0xe0ad78ec, v10
	v_mul_f32_e32 v11, s70, v11
	v_sub_f32_e32 v12, v191, v10
	v_cndmask_b32_e64 v11, -v246, v11, vcc
	v_mul_f32_e32 v12, 0x3e38aa3b, v12
	v_mul_f32_e32 v14, s70, v93
	v_exp_f32_e32 v12, v12
	v_sub_f32_e32 v14, v14, v11
	v_pk_fma_f32 v[98:99], v[98:99], s[70:71], v[10:11] op_sel:[0,0,1] op_sel_hi:[1,0,1] neg_lo:[0,0,1] neg_hi:[0,0,1]
	v_exp_f32_e32 v98, v98
	v_exp_f32_e32 v99, v99
	v_add_f32_e32 v13, 0, v98
	v_pk_fma_f32 v[100:101], v[100:101], s[70:71], v[10:11] op_sel:[0,0,1] op_sel_hi:[1,0,1] neg_lo:[0,0,1] neg_hi:[0,0,1]
	v_exp_f32_e32 v100, v100
	v_add_f32_e32 v13, v99, v13
	v_exp_f32_e32 v101, v101
	v_add_f32_e32 v13, v100, v13
	v_fma_f32 v0, v86, s70, -v11
	v_exp_f32_e32 v0, v0
	v_add_f32_e32 v13, v101, v13
	v_fma_f32 v1, v87, s70, -v11
	v_exp_f32_e32 v1, v1
	v_add_f32_e32 v13, v0, v13
	v_fma_f32 v2, v88, s70, -v11
	v_exp_f32_e32 v2, v2
	v_add_f32_e32 v13, v1, v13
	v_fma_f32 v3, v89, s70, -v11
	v_exp_f32_e32 v3, v3
	v_add_f32_e32 v13, v2, v13
	v_fma_f32 v4, v78, s70, -v11
	v_exp_f32_e32 v4, v4
	v_add_f32_e32 v13, v3, v13
	v_fma_f32 v5, v79, s70, -v11
	v_exp_f32_e32 v5, v5
	v_add_f32_e32 v13, v4, v13
	v_fma_f32 v6, v80, s70, -v11
	v_exp_f32_e32 v6, v6
	v_add_f32_e32 v13, v5, v13
	v_fma_f32 v7, v81, s70, -v11
	v_exp_f32_e32 v7, v7
	v_add_f32_e32 v13, v6, v13
	v_pk_fma_f32 v[90:91], v[90:91], s[70:71], v[10:11] op_sel:[0,0,1] op_sel_hi:[1,0,1] neg_lo:[0,0,1] neg_hi:[0,0,1]
	v_exp_f32_e32 v90, v90
	v_add_f32_e32 v13, v7, v13
	v_exp_f32_e32 v91, v91
	v_add_f32_e32 v13, v90, v13
	v_fma_f32 v92, v92, s70, -v11
	v_exp_f32_e32 v92, v92
	v_add_f32_e32 v13, v91, v13
	v_exp_f32_e32 v93, v14
	v_add_f32_e32 v13, v92, v13
	v_add_f32_e32 v13, v93, v13
	v_fma_f32 v152, v152, v12, v13
	v_pk_mul_f32 v[68:69], v[68:69], v[12:13] op_sel_hi:[1,0]
	v_pk_mul_f32 v[66:67], v[66:67], v[12:13] op_sel_hi:[1,0]
	v_pk_mul_f32 v[60:61], v[60:61], v[12:13] op_sel_hi:[1,0]
	v_pk_mul_f32 v[58:59], v[58:59], v[12:13] op_sel_hi:[1,0]
	v_pk_mul_f32 v[52:53], v[52:53], v[12:13] op_sel_hi:[1,0]
	v_pk_mul_f32 v[50:51], v[50:51], v[12:13] op_sel_hi:[1,0]
	v_pk_mul_f32 v[44:45], v[44:45], v[12:13] op_sel_hi:[1,0]
	v_pk_mul_f32 v[42:43], v[42:43], v[12:13] op_sel_hi:[1,0]
	v_mov_b32_e32 v191, v10
	v_cvt_pk_bf16_f32 v78, v98, v99
	v_cvt_pk_bf16_f32 v79, v100, v101
	v_cvt_pk_bf16_f32 v80, v0, v1
	v_cvt_pk_bf16_f32 v81, v2, v3
	v_cvt_pk_bf16_f32 v86, v4, v5
	v_cvt_pk_bf16_f32 v87, v6, v7
	v_cvt_pk_bf16_f32 v88, v90, v91
	v_cvt_pk_bf16_f32 v89, v92, v93
	s_branch .LBB0_1272
